# v38 + nt on FF2 K-loop A-operand (HID) LDS-DMA loads
# baseline (speedup 1.0000x reference)
.LBB0_615:
	v_add_u32_e32 v151, s51, v149
	ds_read_b128 v[152:155], v151
	ds_read_b128 v[156:159], v151 offset:1024
	ds_read_b128 v[160:163], v151 offset:2048
	ds_read_b128 v[164:167], v151 offset:3072
	v_add_u32_e32 v151, s56, v149
	ds_read_b128 v[168:171], v151
	ds_read_b128 v[172:175], v151 offset:1024
	ds_read_b128 v[176:179], v151 offset:2048
	ds_read_b128 v[180:183], v151 offset:3072
	s_add_u32 s38, s12, s36
	s_addc_u32 s39, s13, s37
	s_cmp_eq_u32 s63, 60
	s_cselect_b32 s42, s59, s38
	s_cselect_b32 s43, s23, s39
	s_cselect_b32 s40, s60, s61
	s_cselect_b32 s41, s21, s62
	s_add_u32 s38, s42, 0x8000
	s_addc_u32 s39, s43, 0
	s_add_i32 m0, s44, 0xc000
	ds_read_b128 v[184:187], v150
	ds_read_b128 v[188:191], v150 offset:1024
	ds_read_b128 v[192:195], v150 offset:2048
	ds_read_b128 v[196:199], v150 offset:3072
	ds_read_b128 v[200:203], v150 offset:4096
	ds_read_b128 v[204:207], v150 offset:5120
	ds_read_b128 v[208:211], v150 offset:6144
	ds_read_b128 v[212:215], v150 offset:7168
	global_load_lds_dwordx4 v146, s[12:13] nt
	s_add_i32 m0, s44, 0xe000
	s_nop 0
	global_load_lds_dwordx4 v144, s[12:13] nt
	s_waitcnt vmcnt(8)
	s_waitcnt lgkmcnt(0)
	s_barrier
	s_setprio 1
	s_waitcnt lgkmcnt(0)
	v_mfma_f32_16x16x32_bf16 v[124:127], v[152:155], v[184:187], v[124:127]
	v_mfma_f32_16x16x32_bf16 v[120:123], v[160:163], v[184:187], v[120:123]
	v_mfma_f32_16x16x32_bf16 v[108:111], v[152:155], v[192:195], v[108:111]
	v_mfma_f32_16x16x32_bf16 v[104:107], v[160:163], v[192:195], v[104:107]
	v_mfma_f32_16x16x32_bf16 v[92:95], v[152:155], v[200:203], v[92:95]
	v_mfma_f32_16x16x32_bf16 v[88:91], v[160:163], v[200:203], v[88:91]
	v_mfma_f32_16x16x32_bf16 v[76:79], v[152:155], v[208:211], v[76:79]
	v_mfma_f32_16x16x32_bf16 v[72:75], v[160:163], v[208:211], v[72:75]
	v_mfma_f32_16x16x32_bf16 v[124:127], v[156:159], v[188:191], v[124:127]
	v_mfma_f32_16x16x32_bf16 v[120:123], v[164:167], v[188:191], v[120:123]
	v_mfma_f32_16x16x32_bf16 v[108:111], v[156:159], v[196:199], v[108:111]
	v_mfma_f32_16x16x32_bf16 v[104:107], v[164:167], v[196:199], v[104:107]
	v_mfma_f32_16x16x32_bf16 v[92:95], v[156:159], v[204:207], v[92:95]
	v_mfma_f32_16x16x32_bf16 v[88:91], v[164:167], v[204:207], v[88:91]
	v_mfma_f32_16x16x32_bf16 v[76:79], v[156:159], v[212:215], v[76:79]
	v_mfma_f32_16x16x32_bf16 v[72:75], v[164:167], v[212:215], v[72:75]
	s_setprio 0
	s_setprio 1
	v_mfma_f32_16x16x32_bf16 v[116:119], v[168:171], v[184:187], v[116:119]
	v_mfma_f32_16x16x32_bf16 v[112:115], v[176:179], v[184:187], v[112:115]
	v_mfma_f32_16x16x32_bf16 v[100:103], v[168:171], v[192:195], v[100:103]
	v_mfma_f32_16x16x32_bf16 v[96:99], v[176:179], v[192:195], v[96:99]
	v_mfma_f32_16x16x32_bf16 v[84:87], v[168:171], v[200:203], v[84:87]
	v_mfma_f32_16x16x32_bf16 v[80:83], v[176:179], v[200:203], v[80:83]
	v_mfma_f32_16x16x32_bf16 v[68:71], v[168:171], v[208:211], v[68:71]
	v_mfma_f32_16x16x32_bf16 v[64:67], v[176:179], v[208:211], v[64:67]
	v_mfma_f32_16x16x32_bf16 v[116:119], v[172:175], v[188:191], v[116:119]
	v_mfma_f32_16x16x32_bf16 v[112:115], v[180:183], v[188:191], v[112:115]
	v_mfma_f32_16x16x32_bf16 v[100:103], v[172:175], v[196:199], v[100:103]
	v_mfma_f32_16x16x32_bf16 v[96:99], v[180:183], v[196:199], v[96:99]
	v_mfma_f32_16x16x32_bf16 v[84:87], v[172:175], v[204:207], v[84:87]
	v_mfma_f32_16x16x32_bf16 v[80:83], v[180:183], v[204:207], v[80:83]
	v_mfma_f32_16x16x32_bf16 v[68:71], v[172:175], v[212:215], v[68:71]
	v_mfma_f32_16x16x32_bf16 v[64:67], v[180:183], v[212:215], v[64:67]
	s_setprio 0
	s_barrier
	s_add_i32 s64, s51, s35
	s_mov_b32 m0, s64
	ds_read_b128 v[184:187], v150 offset:16384
	ds_read_b128 v[188:191], v150 offset:17408
	ds_read_b128 v[192:195], v150 offset:18432
	ds_read_b128 v[196:199], v150 offset:19456
	ds_read_b128 v[200:203], v150 offset:20480
	ds_read_b128 v[204:207], v150 offset:21504
	ds_read_b128 v[208:211], v150 offset:22528
	ds_read_b128 v[212:215], v150 offset:23552
	global_load_lds_dwordx4 v130, s[40:41]
	s_add_i32 m0, s64, 0x2000
	s_add_u32 s64, s40, 0x100000
	v_lshl_add_u64 v[218:219], s[40:41], 0, v[134:135]
	s_addc_u32 s65, s41, 0
	s_add_i32 s66, s56, s35
	global_load_lds_dwordx4 v[218:219], off
	s_mov_b32 m0, s66
	s_nop 0
	global_load_lds_dwordx4 v130, s[64:65]
	s_add_i32 m0, s66, 0x2000
	s_nop 0
	global_load_lds_dwordx4 v134, s[64:65]
	s_mov_b32 m0, s44
	s_nop 0
	global_load_lds_dwordx4 v128, s[42:43] nt
	s_mov_b32 m0, s45
	s_nop 0
	global_load_lds_dwordx4 v132, s[42:43] nt
	s_waitcnt vmcnt(8)
	s_waitcnt lgkmcnt(0)
	s_barrier
	s_setprio 1
	s_waitcnt lgkmcnt(0)
	v_mfma_f32_16x16x32_bf16 v[60:63], v[152:155], v[184:187], v[60:63]
	v_mfma_f32_16x16x32_bf16 v[56:59], v[160:163], v[184:187], v[56:59]
	v_mfma_f32_16x16x32_bf16 v[44:47], v[152:155], v[192:195], v[44:47]
	v_mfma_f32_16x16x32_bf16 v[40:43], v[160:163], v[192:195], v[40:43]
	v_mfma_f32_16x16x32_bf16 v[28:31], v[152:155], v[200:203], v[28:31]
	v_mfma_f32_16x16x32_bf16 v[24:27], v[160:163], v[200:203], v[24:27]
	v_mfma_f32_16x16x32_bf16 v[12:15], v[152:155], v[208:211], v[12:15]
	v_mfma_f32_16x16x32_bf16 v[8:11], v[160:163], v[208:211], v[8:11]
	v_mfma_f32_16x16x32_bf16 v[60:63], v[156:159], v[188:191], v[60:63]
	v_mfma_f32_16x16x32_bf16 v[56:59], v[164:167], v[188:191], v[56:59]
	v_mfma_f32_16x16x32_bf16 v[44:47], v[156:159], v[196:199], v[44:47]
	v_mfma_f32_16x16x32_bf16 v[40:43], v[164:167], v[196:199], v[40:43]
	v_mfma_f32_16x16x32_bf16 v[28:31], v[156:159], v[204:207], v[28:31]
	v_mfma_f32_16x16x32_bf16 v[24:27], v[164:167], v[204:207], v[24:27]
	v_mfma_f32_16x16x32_bf16 v[12:15], v[156:159], v[212:215], v[12:15]
	v_mfma_f32_16x16x32_bf16 v[8:11], v[164:167], v[212:215], v[8:11]
	s_setprio 0
	s_setprio 1
	v_mfma_f32_16x16x32_bf16 v[52:55], v[168:171], v[184:187], v[52:55]
	v_mfma_f32_16x16x32_bf16 v[48:51], v[176:179], v[184:187], v[48:51]
	v_mfma_f32_16x16x32_bf16 v[36:39], v[168:171], v[192:195], v[36:39]
	v_mfma_f32_16x16x32_bf16 v[32:35], v[176:179], v[192:195], v[32:35]
	v_mfma_f32_16x16x32_bf16 v[20:23], v[168:171], v[200:203], v[20:23]
	v_mfma_f32_16x16x32_bf16 v[16:19], v[176:179], v[200:203], v[16:19]
	v_mfma_f32_16x16x32_bf16 v[4:7], v[168:171], v[208:211], v[4:7]
	v_mfma_f32_16x16x32_bf16 v[0:3], v[176:179], v[208:211], v[0:3]
	v_mfma_f32_16x16x32_bf16 v[52:55], v[172:175], v[188:191], v[52:55]
	v_mfma_f32_16x16x32_bf16 v[48:51], v[180:183], v[188:191], v[48:51]
	v_mfma_f32_16x16x32_bf16 v[36:39], v[172:175], v[196:199], v[36:39]
	v_mfma_f32_16x16x32_bf16 v[32:35], v[180:183], v[196:199], v[32:35]
	v_mfma_f32_16x16x32_bf16 v[20:23], v[172:175], v[204:207], v[20:23]
	v_mfma_f32_16x16x32_bf16 v[16:19], v[180:183], v[204:207], v[16:19]
	v_mfma_f32_16x16x32_bf16 v[4:7], v[172:175], v[212:215], v[4:7]
	v_mfma_f32_16x16x32_bf16 v[0:3], v[180:183], v[212:215], v[0:3]
	s_setprio 0
	s_barrier
	s_add_i32 s64, 0, 0x18000
	v_add_u32_e32 v151, s64, v149
	s_add_i32 s65, 0, 0x1c000
	ds_read_b128 v[152:155], v151
	ds_read_b128 v[156:159], v151 offset:1024
	ds_read_b128 v[160:163], v151 offset:2048
	ds_read_b128 v[164:167], v151 offset:3072
	v_add_u32_e32 v151, s65, v149
	ds_read_b128 v[168:171], v151
	ds_read_b128 v[172:175], v151 offset:1024
	ds_read_b128 v[176:179], v151 offset:2048
	ds_read_b128 v[180:183], v151 offset:3072
	s_add_u32 s42, s42, 0x2000
	s_addc_u32 s43, s43, 0
	s_mov_b32 m0, s46
	ds_read_b128 v[184:187], v150 offset:32768
	ds_read_b128 v[188:191], v150 offset:33792
	ds_read_b128 v[192:195], v150 offset:34816
	ds_read_b128 v[196:199], v150 offset:35840
	ds_read_b128 v[200:203], v150 offset:36864
	ds_read_b128 v[204:207], v150 offset:37888
	ds_read_b128 v[208:211], v150 offset:38912
	ds_read_b128 v[212:215], v150 offset:39936
	global_load_lds_dwordx4 v128, s[42:43] nt
	s_mov_b32 m0, s47
	s_nop 0
	global_load_lds_dwordx4 v132, s[42:43] nt
	s_waitcnt vmcnt(8)
	s_waitcnt lgkmcnt(0)
	s_barrier
	s_setprio 1
	s_waitcnt lgkmcnt(0)
	v_mfma_f32_16x16x32_bf16 v[124:127], v[152:155], v[184:187], v[124:127]
	v_mfma_f32_16x16x32_bf16 v[120:123], v[160:163], v[184:187], v[120:123]
	v_mfma_f32_16x16x32_bf16 v[108:111], v[152:155], v[192:195], v[108:111]
	v_mfma_f32_16x16x32_bf16 v[104:107], v[160:163], v[192:195], v[104:107]
	v_mfma_f32_16x16x32_bf16 v[92:95], v[152:155], v[200:203], v[92:95]
	v_mfma_f32_16x16x32_bf16 v[88:91], v[160:163], v[200:203], v[88:91]
	v_mfma_f32_16x16x32_bf16 v[76:79], v[152:155], v[208:211], v[76:79]
	v_mfma_f32_16x16x32_bf16 v[72:75], v[160:163], v[208:211], v[72:75]
	v_mfma_f32_16x16x32_bf16 v[124:127], v[156:159], v[188:191], v[124:127]
	v_mfma_f32_16x16x32_bf16 v[120:123], v[164:167], v[188:191], v[120:123]
	v_mfma_f32_16x16x32_bf16 v[108:111], v[156:159], v[196:199], v[108:111]
	v_mfma_f32_16x16x32_bf16 v[104:107], v[164:167], v[196:199], v[104:107]
	v_mfma_f32_16x16x32_bf16 v[92:95], v[156:159], v[204:207], v[92:95]
	v_mfma_f32_16x16x32_bf16 v[88:91], v[164:167], v[204:207], v[88:91]
	v_mfma_f32_16x16x32_bf16 v[76:79], v[156:159], v[212:215], v[76:79]
	v_mfma_f32_16x16x32_bf16 v[72:75], v[164:167], v[212:215], v[72:75]
	s_setprio 0
	s_setprio 1
	v_mfma_f32_16x16x32_bf16 v[116:119], v[168:171], v[184:187], v[116:119]
	v_mfma_f32_16x16x32_bf16 v[112:115], v[176:179], v[184:187], v[112:115]
	v_mfma_f32_16x16x32_bf16 v[100:103], v[168:171], v[192:195], v[100:103]
	v_mfma_f32_16x16x32_bf16 v[96:99], v[176:179], v[192:195], v[96:99]
	v_mfma_f32_16x16x32_bf16 v[84:87], v[168:171], v[200:203], v[84:87]
	v_mfma_f32_16x16x32_bf16 v[80:83], v[176:179], v[200:203], v[80:83]
	v_mfma_f32_16x16x32_bf16 v[68:71], v[168:171], v[208:211], v[68:71]
	v_mfma_f32_16x16x32_bf16 v[64:67], v[176:179], v[208:211], v[64:67]
	v_mfma_f32_16x16x32_bf16 v[116:119], v[172:175], v[188:191], v[116:119]
	v_mfma_f32_16x16x32_bf16 v[112:115], v[180:183], v[188:191], v[112:115]
	v_mfma_f32_16x16x32_bf16 v[100:103], v[172:175], v[196:199], v[100:103]
	v_mfma_f32_16x16x32_bf16 v[96:99], v[180:183], v[196:199], v[96:99]
	v_mfma_f32_16x16x32_bf16 v[84:87], v[172:175], v[204:207], v[84:87]
	v_mfma_f32_16x16x32_bf16 v[80:83], v[180:183], v[204:207], v[80:83]
	v_mfma_f32_16x16x32_bf16 v[68:71], v[172:175], v[212:215], v[68:71]
	v_mfma_f32_16x16x32_bf16 v[64:67], v[180:183], v[212:215], v[64:67]
	s_setprio 0
	s_barrier
	s_add_u32 s98, s40, s16
	s_addc_u32 s99, s41, s17
	s_add_i32 s42, s64, s35
	s_mov_b32 m0, s42
	ds_read_b128 v[184:187], v150 offset:49152
	ds_read_b128 v[188:191], v150 offset:50176
	ds_read_b128 v[192:195], v150 offset:51200
	ds_read_b128 v[196:199], v150 offset:52224
	ds_read_b128 v[200:203], v150 offset:53248
	ds_read_b128 v[204:207], v150 offset:54272
	ds_read_b128 v[208:211], v150 offset:55296
	ds_read_b128 v[212:215], v150 offset:56320
	global_load_lds_dwordx4 v130, s[98:99]
	s_add_i32 m0, s42, 0x2000
	s_add_u32 s40, s40, 0x100080
	v_lshl_add_u64 v[216:217], v[218:219], 0, s[16:17]
	s_addc_u32 s41, s41, 0
	s_add_i32 s42, s65, s35
	global_load_lds_dwordx4 v[216:217], off
	s_mov_b32 m0, s42
	s_nop 0
	global_load_lds_dwordx4 v130, s[40:41]
	s_add_i32 m0, s42, 0x2000
	s_nop 0
	global_load_lds_dwordx4 v134, s[40:41]
	s_mov_b32 m0, s48
	s_nop 0
	global_load_lds_dwordx4 v128, s[38:39] nt
	s_mov_b32 m0, s49
	s_nop 0
	global_load_lds_dwordx4 v132, s[38:39] nt
	s_waitcnt vmcnt(8)
	s_waitcnt lgkmcnt(0)
	s_barrier
	s_setprio 1
	s_waitcnt lgkmcnt(0)
	v_mfma_f32_16x16x32_bf16 v[60:63], v[152:155], v[184:187], v[60:63]
	v_mfma_f32_16x16x32_bf16 v[56:59], v[160:163], v[184:187], v[56:59]
	v_mfma_f32_16x16x32_bf16 v[44:47], v[152:155], v[192:195], v[44:47]
	v_mfma_f32_16x16x32_bf16 v[40:43], v[160:163], v[192:195], v[40:43]
	v_mfma_f32_16x16x32_bf16 v[28:31], v[152:155], v[200:203], v[28:31]
	v_mfma_f32_16x16x32_bf16 v[24:27], v[160:163], v[200:203], v[24:27]
	v_mfma_f32_16x16x32_bf16 v[12:15], v[152:155], v[208:211], v[12:15]
	v_mfma_f32_16x16x32_bf16 v[8:11], v[160:163], v[208:211], v[8:11]
	v_mfma_f32_16x16x32_bf16 v[60:63], v[156:159], v[188:191], v[60:63]
	v_mfma_f32_16x16x32_bf16 v[56:59], v[164:167], v[188:191], v[56:59]
	v_mfma_f32_16x16x32_bf16 v[44:47], v[156:159], v[196:199], v[44:47]
	v_mfma_f32_16x16x32_bf16 v[40:43], v[164:167], v[196:199], v[40:43]
	v_mfma_f32_16x16x32_bf16 v[28:31], v[156:159], v[204:207], v[28:31]
	v_mfma_f32_16x16x32_bf16 v[24:27], v[164:167], v[204:207], v[24:27]
	v_mfma_f32_16x16x32_bf16 v[12:15], v[156:159], v[212:215], v[12:15]
	v_mfma_f32_16x16x32_bf16 v[8:11], v[164:167], v[212:215], v[8:11]
	s_setprio 0
	s_setprio 1
	v_mfma_f32_16x16x32_bf16 v[52:55], v[168:171], v[184:187], v[52:55]
	v_mfma_f32_16x16x32_bf16 v[48:51], v[176:179], v[184:187], v[48:51]
	v_mfma_f32_16x16x32_bf16 v[36:39], v[168:171], v[192:195], v[36:39]
	v_mfma_f32_16x16x32_bf16 v[32:35], v[176:179], v[192:195], v[32:35]
	v_mfma_f32_16x16x32_bf16 v[20:23], v[168:171], v[200:203], v[20:23]
	v_mfma_f32_16x16x32_bf16 v[16:19], v[176:179], v[200:203], v[16:19]
	v_mfma_f32_16x16x32_bf16 v[4:7], v[168:171], v[208:211], v[4:7]
	v_mfma_f32_16x16x32_bf16 v[0:3], v[176:179], v[208:211], v[0:3]
	v_mfma_f32_16x16x32_bf16 v[52:55], v[172:175], v[188:191], v[52:55]
	v_mfma_f32_16x16x32_bf16 v[48:51], v[180:183], v[188:191], v[48:51]
	v_mfma_f32_16x16x32_bf16 v[36:39], v[172:175], v[196:199], v[36:39]
	v_mfma_f32_16x16x32_bf16 v[32:35], v[180:183], v[196:199], v[32:35]
	v_mfma_f32_16x16x32_bf16 v[20:23], v[172:175], v[204:207], v[20:23]
	v_mfma_f32_16x16x32_bf16 v[16:19], v[180:183], v[204:207], v[16:19]
	v_mfma_f32_16x16x32_bf16 v[4:7], v[172:175], v[212:215], v[4:7]
	v_mfma_f32_16x16x32_bf16 v[0:3], v[180:183], v[212:215], v[0:3]
	s_setprio 0
	s_barrier
	s_add_i32 s63, s63, 2
	s_add_u32 s61, s61, 0x100
	s_addc_u32 s62, s62, 0
	s_add_u32 s36, s36, 0x10000
	s_addc_u32 s37, s37, 0
	v_lshl_add_u64 v[146:147], v[146:147], 0, s[18:19]
	s_cmp_gt_u32 s63, 61
	v_lshl_add_u64 v[144:145], v[144:145], 0, s[18:19]
	s_cbranch_scc0 .LBB0_615
	s_andn2_b64 vcc, exec, s[4:5]
	s_cbranch_vccnz .LBB0_607
	v_mov_b32_e32 v0, 0
	s_mov_b32 s8, s20
	s_mov_b32 s6, s22
	s_mov_b64 s[10:11], s[28:29]
	s_mov_b64 s[12:13], s[26:27]
	s_mov_b32 s50, s57
	v_mov_b32_e32 v1, v0
	v_mov_b32_e32 v2, v0
	v_mov_b32_e32 v3, v0
	v_mov_b32_e32 v4, v0
	v_mov_b32_e32 v5, v0
	v_mov_b32_e32 v6, v0
	v_mov_b32_e32 v7, v0
	v_mov_b32_e32 v16, v0
	v_mov_b32_e32 v17, v0
	v_mov_b32_e32 v18, v0
	v_mov_b32_e32 v19, v0
	v_mov_b32_e32 v20, v0
	v_mov_b32_e32 v21, v0
	v_mov_b32_e32 v22, v0
	v_mov_b32_e32 v23, v0
	v_mov_b32_e32 v32, v0
	v_mov_b32_e32 v33, v0
	v_mov_b32_e32 v34, v0
	v_mov_b32_e32 v35, v0
	v_mov_b32_e32 v36, v0
	v_mov_b32_e32 v37, v0
	v_mov_b32_e32 v38, v0
	v_mov_b32_e32 v39, v0
	v_mov_b32_e32 v48, v0
	v_mov_b32_e32 v49, v0
	v_mov_b32_e32 v50, v0
	v_mov_b32_e32 v51, v0
	v_mov_b32_e32 v52, v0
	v_mov_b32_e32 v53, v0
	v_mov_b32_e32 v54, v0
	v_mov_b32_e32 v55, v0
	v_mov_b32_e32 v8, v0
	v_mov_b32_e32 v9, v0
	v_mov_b32_e32 v10, v0
	v_mov_b32_e32 v11, v0
	v_mov_b32_e32 v12, v0
	v_mov_b32_e32 v13, v0
	v_mov_b32_e32 v14, v0
	v_mov_b32_e32 v15, v0
	v_mov_b32_e32 v24, v0
	v_mov_b32_e32 v25, v0
	v_mov_b32_e32 v26, v0
	v_mov_b32_e32 v27, v0
	v_mov_b32_e32 v28, v0
	v_mov_b32_e32 v29, v0
	v_mov_b32_e32 v30, v0
	v_mov_b32_e32 v31, v0
	v_mov_b32_e32 v40, v0
	v_mov_b32_e32 v41, v0
	v_mov_b32_e32 v42, v0
	v_mov_b32_e32 v43, v0
	v_mov_b32_e32 v44, v0
	v_mov_b32_e32 v45, v0
	v_mov_b32_e32 v46, v0
	v_mov_b32_e32 v47, v0
	v_mov_b32_e32 v56, v0
	v_mov_b32_e32 v57, v0
	v_mov_b32_e32 v58, v0
	v_mov_b32_e32 v59, v0
	v_mov_b32_e32 v60, v0
	v_mov_b32_e32 v61, v0
	v_mov_b32_e32 v62, v0
	v_mov_b32_e32 v63, v0
	v_mov_b32_e32 v64, v0
	v_mov_b32_e32 v65, v0
	v_mov_b32_e32 v66, v0
	v_mov_b32_e32 v67, v0
	v_mov_b32_e32 v68, v0
	v_mov_b32_e32 v69, v0
	v_mov_b32_e32 v70, v0
	v_mov_b32_e32 v71, v0
	v_mov_b32_e32 v80, v0
	v_mov_b32_e32 v81, v0
	v_mov_b32_e32 v82, v0
	v_mov_b32_e32 v83, v0
	v_mov_b32_e32 v84, v0
	v_mov_b32_e32 v85, v0
	v_mov_b32_e32 v86, v0
	v_mov_b32_e32 v87, v0
	v_mov_b32_e32 v96, v0
	v_mov_b32_e32 v97, v0
	v_mov_b32_e32 v98, v0
	v_mov_b32_e32 v99, v0
	v_mov_b32_e32 v100, v0
	v_mov_b32_e32 v101, v0
	v_mov_b32_e32 v102, v0
	v_mov_b32_e32 v103, v0
	v_mov_b32_e32 v112, v0
	v_mov_b32_e32 v113, v0
	v_mov_b32_e32 v114, v0
	v_mov_b32_e32 v115, v0
	v_mov_b32_e32 v116, v0
	v_mov_b32_e32 v117, v0
	v_mov_b32_e32 v118, v0
	v_mov_b32_e32 v119, v0
	v_mov_b32_e32 v72, v0
	v_mov_b32_e32 v73, v0
	v_mov_b32_e32 v74, v0
	v_mov_b32_e32 v75, v0
	v_mov_b32_e32 v76, v0
	v_mov_b32_e32 v77, v0
	v_mov_b32_e32 v78, v0
	v_mov_b32_e32 v79, v0
	v_mov_b32_e32 v88, v0
	v_mov_b32_e32 v89, v0
	v_mov_b32_e32 v90, v0
	v_mov_b32_e32 v91, v0
	v_mov_b32_e32 v92, v0
	v_mov_b32_e32 v93, v0
	v_mov_b32_e32 v94, v0
	v_mov_b32_e32 v95, v0
	v_mov_b32_e32 v104, v0
	v_mov_b32_e32 v105, v0
	v_mov_b32_e32 v106, v0
	v_mov_b32_e32 v107, v0
	v_mov_b32_e32 v108, v0
	v_mov_b32_e32 v109, v0
	v_mov_b32_e32 v110, v0
	v_mov_b32_e32 v111, v0
	v_mov_b32_e32 v120, v0
	v_mov_b32_e32 v121, v0
	v_mov_b32_e32 v122, v0
	v_mov_b32_e32 v123, v0
	v_mov_b32_e32 v124, v0
	v_mov_b32_e32 v125, v0
	v_mov_b32_e32 v126, v0
	v_mov_b32_e32 v127, v0
	s_branch .LBB0_607
